# attention phases: one static s_setprio 1 for waves 4-7 (younger half), reset at phase end
# baseline (speedup 1.0000x reference)
; DI int tidx() { int t = __builtin_amdgcn_workitem_id_x(); asm volatile("" : "+v"(t)); return t; }
; DI void run_phase(const Params& p, int ph, char* lds, int bid, int nb) {
;     ...
;     int* su = (int*)(lds + LDS_BYTES - 16);
;     for (;;) {
;       __syncthreads();
;       if (tidx() == 0) *su = (int)atomicAdd(p.nmax + 6144 + l, 1u);
;       __syncthreads();
;       const int q = *su;
.LBB0_573:
	s_or_b64 exec, exec, s[0:1]
	v_readlane_b32 s0, v252, 0
	v_readlane_b32 s2, v252, 2
	v_readlane_b32 s4, v252, 4
	v_readlane_b32 s3, v252, 3
	v_readlane_b32 s5, v252, 5
	s_add_u32 s2, s4, 0x6000
	s_addc_u32 s3, s5, 0
	v_readlane_b32 s6, v252, 6
	v_readlane_b32 s7, v252, 7
	v_readlane_b32 s8, v252, 8
	v_readlane_b32 s9, v252, 9
	v_readlane_b32 s10, v252, 10
	v_readlane_b32 s11, v252, 11
	s_add_u32 s0, s4, 0x4000
	v_writelane_b32 v253, s0, 23
	s_addc_u32 s0, s5, 0
	v_readlane_b32 s4, v252, 36
	v_readlane_b32 s6, v252, 38
	v_writelane_b32 v253, s0, 25
	v_readlane_b32 s7, v252, 39
	s_add_u32 s0, s6, 0x100
	v_writelane_b32 v254, s0, 63
	s_addc_u32 s0, s7, 0
	s_waitcnt lgkmcnt(0)
	v_mbcnt_lo_u32_b32 v0, -1, 0
	v_readlane_b32 s12, v252, 12
	v_readlane_b32 s13, v252, 13
	v_readlane_b32 s14, v252, 14
	v_readlane_b32 s15, v252, 15
	v_readlane_b32 s5, v252, 37
	v_readlane_b32 s10, v252, 42
	v_readlane_b32 s11, v252, 43
	v_writelane_b32 v255, s0, 0
	s_add_u32 s0, s4, 0x100
	v_mbcnt_hi_u32_b32 v207, -1, v0
	v_readlane_b32 s8, v252, 40
	v_readlane_b32 s9, v252, 41
	v_writelane_b32 v255, s0, 1
	s_addc_u32 s0, s5, 0
	s_mov_b32 s6, 0x41000000
	s_mov_b32 s10, 0x3f828f5c
	s_mov_b32 s12, 2.0
	s_mov_b32 s14, 0x41200000
	s_mov_b32 s34, 0x41800000
	s_mov_b32 s44, 0x41900000
	s_mov_b32 s46, 0x41c00000
	s_mov_b32 s48, 0x41d00000
	s_mov_b32 s16, 0x42280000
	s_mov_b32 s18, 0x42200000
	s_mov_b32 s20, 0x42080000
	s_mov_b32 s22, 0x42000000
	v_and_b32_e32 v0, 64, v207
	v_writelane_b32 v255, s0, 2
	s_mov_b32 s5, 0
	v_mov_b32_e32 v113, 0
	v_mov_b32_e32 v166, 0x1fff0
	s_movk_i32 s72, 0x1600
	s_movk_i32 s73, 0x90
	s_mov_b32 s7, 0x41100000
	s_mov_b64 s[8:9], 0x80
	s_movk_i32 s74, 0x1000
	s_mov_b32 s75, 0xf800000
	v_mov_b32_e32 v167, 0x260
	s_mov_b32 s11, 0x3fb8aa3b
	s_mov_b32 s24, 0xc2200000
	s_mov_b32 s13, 0x40400000
	s_mov_b32 s15, 0x41300000
	s_mov_b32 s35, 0x41880000
	s_mov_b32 s45, 0x41980000
	s_mov_b32 s47, 0x41c80000
	s_mov_b32 s49, 0x41d80000
	s_mov_b32 s17, 0x422c0000
	s_mov_b32 s19, 0x42240000
	s_mov_b32 s21, 0x420c0000
	s_mov_b32 s23, 0x42040000
	v_mov_b32_e32 v115, 0x41000000
	s_mov_b32 s25, 0xc2ce8ed0
	s_mov_b32 s26, 0x42b17218
	v_mov_b32_e32 v168, 0x358637bd
	s_mov_b32 s27, 0x80000
	s_mov_b32 s28, 0x100000
	s_mov_b32 s29, 0xc2fc0000
	s_mov_b32 s30, 0x1000000
	s_brev_b32 s31, 64
	v_xor_b32_e32 v209, 32, v207
	v_add_u32_e32 v208, 64, v0
	v_mov_b32_e32 v169, 0x42800000
	v_mov_b32_e32 v170, 0x7f800000
	v_not_b32_e32 v171, 63
	s_barrier
	v_readfirstlane_b32 s98, v206
	s_nop 3
	s_cmp_ge_u32 s98, 0x100
	s_cbranch_scc0 .Lprio_a0
	s_setprio 1
.Lprio_a0:
	v_readlane_b32 s1, v252, 1
	s_branch .LBB0_576

; __device__ __forceinline__ void xcd_barrier(const XcdBarrier& b) {
;     asm volatile("s_waitcnt vmcnt(0)" ::: "memory");
;     __syncthreads();
;     if (threadIdx.x == 0) {
;         unsigned* bar = b.bar;
;         __builtin_amdgcn_s_waitcnt(0);
;         unsigned nloc = b.st[0], nx = b.st[1];
;         if (nloc == 0u) { xcd_barrier_complete(bar, b.x, nloc, nx); b.st[0] = nloc; b.st[1] = nx; }
.LBB0_651:
	s_setprio 0
	s_waitcnt vmcnt(0)
	s_barrier
	s_mov_b64 s[0:1], exec
	v_readlane_b32 s4, v251, 19
	v_readlane_b32 s2, v252, 34
	v_readlane_b32 s18, v251, 33
	v_readlane_b32 s19, v251, 34
	v_readlane_b32 s3, v252, 35
	v_readlane_b32 s8, v251, 23
	v_readlane_b32 s9, v251, 24
	v_readlane_b32 s10, v251, 25
	v_readlane_b32 s11, v251, 26
	v_readlane_b32 s12, v251, 27
	v_readlane_b32 s13, v251, 28
	v_readlane_b32 s14, v251, 29
	v_readlane_b32 s15, v251, 30
	v_readlane_b32 s16, v251, 31
	v_readlane_b32 s17, v251, 32
	s_mov_b64 s[90:91], s[18:19]
	s_and_b64 s[2:3], s[0:1], s[2:3]
	v_readlane_b32 s79, v251, 18
	s_mov_b64 s[88:89], s[16:17]
	s_mov_b64 s[86:87], s[14:15]
	s_mov_b64 s[84:85], s[12:13]
	s_mov_b64 s[82:83], s[10:11]
	s_mov_b64 s[80:81], s[8:9]
	v_readlane_b32 s5, v251, 20
	v_readlane_b32 s6, v251, 21
	v_readlane_b32 s7, v251, 22
	s_mov_b64 exec, s[2:3]
	s_cbranch_execz .LBB0_703
	v_mov_b32_e32 v0, 0x24800
	s_waitcnt vmcnt(0) expcnt(0) lgkmcnt(0)
	ds_read_b32 v2, v0
	v_mov_b32_e32 v0, 0x24804
	ds_read_b32 v0, v0
	s_waitcnt lgkmcnt(1)
	v_cmp_ne_u32_e32 vcc, 0, v2
	s_cbranch_vccnz .LBB0_667
	v_readlane_b32 s8, v252, 0
	v_readlane_b32 s2, v252, 16
	s_mov_b64 s[4:5], s[38:39]
	v_readlane_b32 s10, v252, 2
	s_mul_i32 s33, s5, s2
	v_readlane_b32 s11, v252, 3
	s_add_u32 s2, s10, 0x1000
	s_addc_u32 s3, s11, 0
	s_mul_i32 s33, s33, s4
	s_add_u32 s4, s10, 0x1100
	s_addc_u32 s5, s11, 0
	s_add_u32 s6, s10, 0x1200
	s_addc_u32 s7, s11, 0
	v_readlane_b32 s9, v252, 1
	s_add_u32 s8, s10, 0x1300
	s_addc_u32 s9, s11, 0
	s_mov_b32 s34, 1
	v_mov_b32_e32 v16, 0
	v_readlane_b32 s12, v252, 4
	v_readlane_b32 s13, v252, 5
	v_readlane_b32 s14, v252, 6
	v_readlane_b32 s15, v252, 7
	v_readlane_b32 s16, v252, 8
	v_readlane_b32 s17, v252, 9
	v_readlane_b32 s18, v252, 10
	v_readlane_b32 s19, v252, 11
	v_readlane_b32 s20, v252, 12
	v_readlane_b32 s21, v252, 13
	v_readlane_b32 s22, v252, 14
	v_readlane_b32 s23, v252, 15
	s_branch .LBB0_655

; DI int tidx() { int t = __builtin_amdgcn_workitem_id_x(); asm volatile("" : "+v"(t)); return t; }
; DI void run_phase(const Params& p, int ph, char* lds, int bid, int nb) {
;     ...
;     int* su = (int*)(lds + LDS_BYTES - 16);
;     for (;;) {
;       __syncthreads();
;       if (tidx() == 0) *su = (int)atomicAdd(p.nmax + 6144 + l, 1u);
;       __syncthreads();
;       const int q = *su;
.LBB0_1550:
	s_or_b64 exec, exec, s[0:1]
	v_readlane_b32 s0, v252, 0
	v_readlane_b32 s2, v252, 2
	v_readlane_b32 s4, v252, 4
	v_readlane_b32 s6, v252, 6
	v_readlane_b32 s7, v252, 7
	v_readlane_b32 s3, v252, 3
	v_readlane_b32 s5, v252, 5
	s_add_u32 s2, s4, 0x6004
	s_mov_b32 s6, 0x41000000
	s_mov_b32 s28, 0x3f828f5c
	s_mov_b32 s30, 2.0
	s_mov_b32 s36, 0x41200000
	s_mov_b32 s34, 0x41800000
	s_mov_b32 s44, 0x41900000
	s_mov_b32 s46, 0x41c00000
	s_mov_b32 s48, 0x41d00000
	s_mov_b32 s86, 0x42680000
	s_mov_b32 s92, 0x42600000
	s_mov_b32 s38, 0x42400000
	s_mov_b32 s40, 0x42280000
	s_mov_b32 s42, 0x42200000
	s_mov_b32 s84, 0x42080000
	s_mov_b32 s24, 0x42000000
	s_addc_u32 s3, s5, 0
	s_mov_b32 s5, 0
	v_mov_b32_e32 v113, 0
	v_mov_b32_e32 v166, 0x1fff0
	s_movk_i32 s72, 0x1600
	s_movk_i32 s73, 0x90
	s_mov_b32 s7, 0x41100000
	s_mov_b64 s[26:27], 0x80
	s_movk_i32 s74, 0x1000
	s_mov_b32 s75, 0xf800000
	v_mov_b32_e32 v167, 0x260
	s_mov_b32 s29, 0x3fb8aa3b
	s_mov_b32 s76, 0xc2200000
	s_mov_b32 s31, 0x40400000
	s_mov_b32 s37, 0x41300000
	s_mov_b32 s35, 0x41880000
	s_mov_b32 s45, 0x41980000
	s_mov_b32 s47, 0x41c80000
	s_mov_b32 s49, 0x41d80000
	s_mov_b32 s87, 0x426c0000
	s_mov_b32 s93, 0x42640000
	s_mov_b32 s39, 0x42440000
	s_mov_b32 s41, 0x422c0000
	s_mov_b32 s43, 0x42240000
	s_mov_b32 s85, 0x420c0000
	s_mov_b32 s25, 0x42040000
	v_mov_b32_e32 v115, 0x41000000
	s_mov_b32 s77, 0xc2ce8ed0
	s_mov_b32 s78, 0x42b17218
	v_mov_b32_e32 v168, 0x358637bd
	s_mov_b32 s79, 0x80000
	s_mov_b32 s80, 0x100000
	s_mov_b32 s81, 0xc2fc0000
	s_mov_b32 s82, 0x1000000
	s_brev_b32 s83, 64
	v_mov_b32_e32 v169, 0x42800000
	v_mov_b32_e32 v170, 0x7f800000
	v_not_b32_e32 v171, 63
	s_waitcnt lgkmcnt(0)
	s_barrier
	v_readfirstlane_b32 s98, v206
	s_nop 3
	s_cmp_ge_u32 s98, 0x100
	s_cbranch_scc0 .Lprio_a1
	s_setprio 1
.Lprio_a1:
	v_readlane_b32 s1, v252, 1
	v_readlane_b32 s8, v252, 8
	v_readlane_b32 s9, v252, 9
	v_readlane_b32 s10, v252, 10
	v_readlane_b32 s11, v252, 11
	v_readlane_b32 s12, v252, 12
	v_readlane_b32 s13, v252, 13
	v_readlane_b32 s14, v252, 14
	v_readlane_b32 s15, v252, 15
	s_branch .LBB0_1553

; __device__ __forceinline__ void xcd_barrier(const XcdBarrier& b) {
;     asm volatile("s_waitcnt vmcnt(0)" ::: "memory");
;     __syncthreads();
;     if (threadIdx.x == 0) {
;         unsigned* bar = b.bar;
;         __builtin_amdgcn_s_waitcnt(0);
;         unsigned nloc = b.st[0], nx = b.st[1];
;         if (nloc == 0u) { xcd_barrier_complete(bar, b.x, nloc, nx); b.st[0] = nloc; b.st[1] = nx; }
.LBB0_1628:
	s_setprio 0
	s_waitcnt vmcnt(0)
	s_barrier
	s_mov_b64 s[0:1], exec
	v_readlane_b32 s2, v252, 34
	v_readlane_b32 s3, v252, 35
	v_readlane_b32 s84, v255, 7
	s_and_b64 s[2:3], s[0:1], s[2:3]
	v_readlane_b32 s96, v251, 18
	v_readlane_b32 s4, v251, 19
	v_readlane_b32 s85, v255, 8
	v_readlane_b32 s5, v251, 20
	v_readlane_b32 s6, v251, 21
	v_readlane_b32 s7, v251, 22
	v_readlane_b32 s8, v251, 23
	v_readlane_b32 s9, v251, 24
	v_readlane_b32 s10, v251, 25
	v_readlane_b32 s11, v251, 26
	v_readlane_b32 s12, v251, 27
	v_readlane_b32 s13, v251, 28
	v_readlane_b32 s14, v251, 29
	v_readlane_b32 s15, v251, 30
	v_readlane_b32 s16, v251, 31
	v_readlane_b32 s17, v251, 32
	v_readlane_b32 s18, v251, 33
	v_readlane_b32 s19, v251, 34
	s_mov_b64 exec, s[2:3]
	s_cbranch_execz .LBB0_1680
	v_mov_b32_e32 v0, 0x24800
	s_waitcnt vmcnt(0) expcnt(0) lgkmcnt(0)
	ds_read_b32 v2, v0
	v_mov_b32_e32 v0, 0x24804
	ds_read_b32 v0, v0
	s_waitcnt lgkmcnt(1)
	v_cmp_ne_u32_e32 vcc, 0, v2
	s_cbranch_vccnz .LBB0_1644
	v_readlane_b32 s4, v251, 16
	v_readlane_b32 s2, v252, 16
	v_readlane_b32 s5, v251, 17
	s_mul_i32 s20, s5, s2
	s_mul_i32 s20, s20, s4
	v_readlane_b32 s4, v252, 0
	v_readlane_b32 s6, v252, 2
	v_readlane_b32 s7, v252, 3
	v_readlane_b32 s8, v252, 4
	v_readlane_b32 s9, v252, 5
	v_readlane_b32 s10, v252, 6
	v_readlane_b32 s11, v252, 7
	v_readlane_b32 s5, v252, 1
	s_mov_b64 s[10:11], s[6:7]
	s_add_u32 s2, s10, 0x1000
	s_addc_u32 s3, s11, 0
	s_mov_b64 s[8:9], s[4:5]
	s_add_u32 s4, s10, 0x1100
	s_addc_u32 s5, s11, 0
	s_add_u32 s6, s10, 0x1200
	s_addc_u32 s7, s11, 0
	s_add_u32 s8, s10, 0x1300
	s_addc_u32 s9, s11, 0
	s_mov_b32 s21, 1
	v_mov_b32_e32 v16, 0
	v_readlane_b32 s12, v252, 8
	v_readlane_b32 s13, v252, 9
	v_readlane_b32 s14, v252, 10
	v_readlane_b32 s15, v252, 11
	v_readlane_b32 s16, v252, 12
	v_readlane_b32 s17, v252, 13
	v_readlane_b32 s18, v252, 14
	v_readlane_b32 s19, v252, 15
	s_branch .LBB0_1632
